# grid barrier acquire side: the XCD's last arriver invalidates L2 once before publishing; after release every workgroup invalidates only its L1 (buffer_inv sc0) instead of 32 L2 invalidations per XCD
# speedup vs baseline: 1.0114x; 1.0085x over previous
; __device__ __forceinline__ unsigned xb_ld(unsigned* p)              { return __hip_atomic_load(p, __ATOMIC_RELAXED, __HIP_MEMORY_SCOPE_AGENT); }
; __device__ __forceinline__ unsigned xb_add(unsigned* p, unsigned v) { return __hip_atomic_fetch_add(p, v, __ATOMIC_RELAXED, __HIP_MEMORY_SCOPE_AGENT); }
; #define XB_SPIN(cond, bar) do { unsigned _sp = 0; while (cond) { __builtin_amdgcn_s_sleep(1); \
;     if ((++_sp & 255u) == 0u) { if (xb_ld(&(bar)[XB_TMO])) break; if (_sp > XB_SPIN_CAP) { atomicAdd(&(bar)[XB_TMO], 1u); break; } } } } while (0)
; __device__ __forceinline__ void xcd_barrier(const XcdBarrier& b) {
;     ...
;         const unsigned old = xb_add(&bar[XB_XSUB(b.x)], 1u);
;         const unsigned gen = old / nloc;
;         if (old + 1u == (gen + 1u) * nloc) {
;             __builtin_amdgcn_fence(__ATOMIC_RELEASE, "agent");
;             asm volatile("s_waitcnt vmcnt(0)" ::: "memory");
;             const unsigned og = xb_add(&bar[XB_TOP], 1u);
;             const unsigned tg = og / nx;
;             if (og + 1u == (tg + 1u) * nx) xb_add(&bar[XB_TOPGEN], 1u);
;             else XB_SPIN(xb_ld(&bar[XB_TOPGEN]) == tg, bar);
;             __builtin_amdgcn_fence(__ATOMIC_ACQUIRE, "agent");
;             xb_add(&bar[XB_XGEN(b.x)], 1u);
.LBB0_570:
	s_or_b64 exec, exec, s[4:5]
	v_cvt_f32_u32_e32 v5, v2
	s_waitcnt vmcnt(0)
	v_readfirstlane_b32 s4, v4
	v_sub_u32_e32 v4, 0, v2
	v_rcp_iflag_f32_e32 v5, v5
	v_add_u32_e32 v6, s4, v1
	v_mul_f32_e32 v5, 0x4f7ffffe, v5
	v_cvt_u32_f32_e32 v5, v5
	v_mul_lo_u32 v1, v4, v5
	v_mul_hi_u32 v1, v5, v1
	v_add_u32_e32 v1, v5, v1
	v_mul_hi_u32 v1, v6, v1
	v_mul_lo_u32 v4, v1, v2
	v_sub_u32_e32 v4, v6, v4
	v_add_u32_e32 v5, 1, v1
	v_cmp_ge_u32_e32 vcc, v4, v2
	s_nop 1
	v_cndmask_b32_e32 v1, v1, v5, vcc
	v_sub_u32_e32 v5, v4, v2
	v_cndmask_b32_e32 v4, v4, v5, vcc
	v_add_u32_e32 v5, 1, v1
	v_cmp_ge_u32_e32 vcc, v4, v2
	v_add_u32_e32 v4, 1, v6
	s_nop 0
	v_cndmask_b32_e32 v1, v1, v5, vcc
	v_mul_lo_u32 v5, v2, v1
	v_add_u32_e32 v2, v5, v2
	v_cmp_ne_u32_e32 vcc, v4, v2
	s_waitcnt lgkmcnt(0)
	v_readfirstlane_b32 s8, v0
	v_readlane_b32 s6, v253, 63
	v_readlane_b32 s7, v254, 0
	s_mul_i32 s8, s8, s32
	s_add_u32 s6, s6, 0x347a3800
	s_addc_u32 s7, s7, 0
	s_cbranch_vccnz .Lgb_poll
	buffer_wbl2 sc1
	s_waitcnt vmcnt(0)
	buffer_inv sc1
	s_waitcnt vmcnt(0)
	v_mov_b32_e32 v1, 1
	global_atomic_add v3, v1, s[6:7]

; __device__ __forceinline__ unsigned xb_ld(unsigned* p)              { return __hip_atomic_load(p, __ATOMIC_RELAXED, __HIP_MEMORY_SCOPE_AGENT); }
; #define XB_SPIN(cond, bar) do { unsigned _sp = 0; while (cond) { __builtin_amdgcn_s_sleep(1); \
;     if ((++_sp & 255u) == 0u) { if (xb_ld(&(bar)[XB_TMO])) break; if (_sp > XB_SPIN_CAP) { atomicAdd(&(bar)[XB_TMO], 1u); break; } } } } while (0)
; __device__ __forceinline__ void xcd_barrier(const XcdBarrier& b) {
;     ...
;             XB_SPIN(xb_ld(&bar[XB_XGEN(b.x)]) == gen, bar);
;             __builtin_amdgcn_fence(__ATOMIC_ACQUIRE, "agent");
;             asm volatile("s_waitcnt vmcnt(0)" ::: "memory");
;         }
.Lgb_done:
	buffer_inv sc0
	s_waitcnt vmcnt(0)
